# attention fast trip: first QK^T MFMA of each step issued ahead of the step's first two V fragment reads
# speedup vs baseline: 1.0120x; 1.0037x over previous
.Lfast3:
.Lf3_0_485:
	s_waitcnt lgkmcnt(9)
	v_mfma_f32_32x32x16_bf16 v[98:113], v[174:177], v[142:145], v[34:49]
	ds_read_b64_tr_b16 v[178:179], v203 offset:24576
	ds_read_b64_tr_b16 v[180:181], v203 offset:25088
	v_add_f32_e32 v82, v66, v67
	v_add_f32_e32 v82, v68, v82
	v_add_f32_e32 v82, v69, v82
	v_add_f32_e32 v82, v70, v82
	v_add_f32_e32 v82, v71, v82
	v_cvt_pk_bf16_f32 v138, v66, v67
	v_cvt_pk_bf16_f32 v139, v68, v69
	ds_read_b64_tr_b16 v[174:175], v203 offset:28672
	ds_read_b64_tr_b16 v[176:177], v203 offset:29184
	v_add_f32_e32 v66, v72, v82
	s_waitcnt lgkmcnt(10)
	v_mfma_f32_32x32x16_bf16 v[82:97], v[170:173], v[142:145], v[34:49]
	v_add_f32_e32 v66, v73, v66
	v_add_f32_e32 v66, v74, v66
	v_add_f32_e32 v114, v75, v66
	v_cvt_pk_bf16_f32 v140, v70, v71
	v_cvt_pk_bf16_f32 v141, v72, v73
	ds_read_b64_tr_b16 v[66:67], v203 offset:25600
	ds_read_b64_tr_b16 v[68:69], v203 offset:26112
	s_waitcnt lgkmcnt(11)
	v_mfma_f32_32x32x16_bf16 v[98:113], v[166:169], v[134:137], v[98:113]
	v_add_f32_e32 v70, v76, v114
	v_add_f32_e32 v70, v77, v70
	v_add_f32_e32 v70, v78, v70
	v_add_f32_e32 v114, v79, v70
	v_cvt_pk_bf16_f32 v130, v74, v75
	v_cvt_pk_bf16_f32 v131, v76, v77
	ds_read_b64_tr_b16 v[70:71], v203 offset:29696
	ds_read_b64_tr_b16 v[72:73], v203 offset:30208
	s_waitcnt lgkmcnt(12)
	v_mfma_f32_32x32x16_bf16 v[82:97], v[162:165], v[134:137], v[82:97]
	v_add_f32_e32 v74, v80, v114
	v_add_f32_e32 v74, v81, v74
	v_add_f32_e32 v74, v50, v74
	v_add_f32_e32 v114, v51, v74
	v_cvt_pk_bf16_f32 v132, v78, v79
	v_cvt_pk_bf16_f32 v133, v80, v81
	ds_read_b64_tr_b16 v[74:75], v203 offset:26624
	ds_read_b64_tr_b16 v[76:77], v203 offset:27136
	s_waitcnt lgkmcnt(13)
	v_mfma_f32_32x32x16_bf16 v[98:113], v[158:161], v[126:129], v[98:113]
	v_add_f32_e32 v78, v52, v114
	v_add_f32_e32 v78, v53, v78
	v_add_f32_e32 v78, v54, v78
	v_add_f32_e32 v78, v55, v78
	v_cvt_pk_bf16_f32 v122, v50, v51
	v_cvt_pk_bf16_f32 v123, v52, v53
	ds_read_b64_tr_b16 v[50:51], v203 offset:30720
	ds_read_b64_tr_b16 v[52:53], v203 offset:31232
	s_waitcnt lgkmcnt(14)
	v_mfma_f32_32x32x16_bf16 v[82:97], v[154:157], v[126:129], v[82:97]
	v_add_f32_e32 v78, v56, v78
	v_add_f32_e32 v78, v57, v78
	v_add_f32_e32 v78, v58, v78
	v_add_f32_e32 v78, v59, v78
	v_cvt_pk_bf16_f32 v124, v54, v55
	v_cvt_pk_bf16_f32 v125, v56, v57
	ds_read_b64_tr_b16 v[54:55], v203 offset:27648
	ds_read_b64_tr_b16 v[56:57], v203 offset:28160
	s_waitcnt lgkmcnt(14)
	v_mfma_f32_32x32x16_bf16 v[98:113], v[150:153], v[118:121], v[98:113]
	v_add_f32_e32 v78, v60, v78
	v_add_f32_e32 v78, v61, v78
	v_add_f32_e32 v78, v62, v78
	v_add_f32_e32 v78, v63, v78
	v_cvt_pk_bf16_f32 v114, v58, v59
	v_cvt_pk_bf16_f32 v115, v60, v61
	ds_read_b64_tr_b16 v[58:59], v203 offset:31744
	ds_read_b64_tr_b16 v[60:61], v203 offset:32256
	v_mfma_f32_32x32x16_bf16 v[82:97], v[146:149], v[118:121], v[82:97]
	v_add_f32_e32 v78, v64, v78
	v_add_f32_e32 v78, v65, v78
	v_cvt_pk_bf16_f32 v116, v62, v63
	v_cvt_pk_bf16_f32 v117, v64, v65
	s_add_i32 s98, s46, 0x2000
	s_mov_b32 s5, m0
	s_mov_b32 m0, s98
	s_nop 0
	global_load_lds_dwordx4 v188, s[100:101]
	s_mov_b32 m0, s5
	s_add_i32 s98, s47, 0x4000
	s_mov_b32 s5, m0
	s_mov_b32 m0, s98
	s_nop 0
	global_load_lds_dwordx4 v186, s[100:101]
	s_mov_b32 m0, s5
	v_add_f32_e32 v190, v205, v78

.Lf3_0_488:
	s_waitcnt lgkmcnt(9)
	v_mfma_f32_32x32x16_bf16 v[66:81], v[62:65], v[142:145], v[34:49]
	ds_read_b64_tr_b16 v[150:151], v203 offset:32768
	ds_read_b64_tr_b16 v[152:153], v203 offset:33280
	v_add_f32_e32 v50, v98, v99
	v_add_f32_e32 v50, v100, v50
	v_add_f32_e32 v50, v101, v50
	v_add_f32_e32 v50, v102, v50
	v_add_f32_e32 v50, v103, v50
	v_cvt_pk_bf16_f32 v138, v98, v99
	v_cvt_pk_bf16_f32 v139, v100, v101
	ds_read_b64_tr_b16 v[146:147], v203 offset:36864
	ds_read_b64_tr_b16 v[148:149], v203 offset:37376
	v_add_f32_e32 v50, v104, v50
	v_add_f32_e32 v50, v105, v50
	v_add_f32_e32 v50, v106, v50
	v_add_f32_e32 v114, v107, v50
	s_waitcnt lgkmcnt(10)
	v_mfma_f32_32x32x16_bf16 v[50:65], v[174:177], v[142:145], v[34:49]
	v_cvt_pk_bf16_f32 v140, v102, v103
	v_cvt_pk_bf16_f32 v141, v104, v105
	ds_read_b64_tr_b16 v[98:99], v203 offset:33792
	ds_read_b64_tr_b16 v[100:101], v203 offset:34304
	s_waitcnt lgkmcnt(11)
	v_mfma_f32_32x32x16_bf16 v[66:81], v[178:181], v[134:137], v[66:81]
	v_add_f32_e32 v102, v108, v114
	v_add_f32_e32 v102, v109, v102
	v_add_f32_e32 v102, v110, v102
	v_add_f32_e32 v114, v111, v102
	v_cvt_pk_bf16_f32 v130, v106, v107
	v_cvt_pk_bf16_f32 v131, v108, v109
	ds_read_b64_tr_b16 v[102:103], v203 offset:37888
	ds_read_b64_tr_b16 v[104:105], v203 offset:38400
	s_waitcnt lgkmcnt(12)
	v_mfma_f32_32x32x16_bf16 v[50:65], v[170:173], v[134:137], v[50:65]
	v_add_f32_e32 v106, v112, v114
	v_add_f32_e32 v106, v113, v106
	v_add_f32_e32 v106, v82, v106
	v_add_f32_e32 v114, v83, v106
	v_cvt_pk_bf16_f32 v132, v110, v111
	v_cvt_pk_bf16_f32 v133, v112, v113
	ds_read_b64_tr_b16 v[106:107], v203 offset:34816
	ds_read_b64_tr_b16 v[108:109], v203 offset:35328
	s_waitcnt lgkmcnt(13)
	v_mfma_f32_32x32x16_bf16 v[66:81], v[166:169], v[126:129], v[66:81]
	v_add_f32_e32 v110, v84, v114
	v_add_f32_e32 v110, v85, v110
	v_add_f32_e32 v110, v86, v110
	v_add_f32_e32 v110, v87, v110
	v_cvt_pk_bf16_f32 v122, v82, v83
	v_cvt_pk_bf16_f32 v123, v84, v85
	ds_read_b64_tr_b16 v[82:83], v203 offset:38912
	ds_read_b64_tr_b16 v[84:85], v203 offset:39424
	s_waitcnt lgkmcnt(14)
	v_mfma_f32_32x32x16_bf16 v[50:65], v[162:165], v[126:129], v[50:65]
	v_add_f32_e32 v110, v88, v110
	v_add_f32_e32 v110, v89, v110
	v_add_f32_e32 v110, v90, v110
	v_add_f32_e32 v110, v91, v110
	v_cvt_pk_bf16_f32 v124, v86, v87
	v_cvt_pk_bf16_f32 v125, v88, v89
	ds_read_b64_tr_b16 v[86:87], v203 offset:35840
	ds_read_b64_tr_b16 v[88:89], v203 offset:36352
	s_waitcnt lgkmcnt(14)
	v_mfma_f32_32x32x16_bf16 v[66:81], v[158:161], v[118:121], v[66:81]
	v_add_f32_e32 v110, v92, v110
	v_add_f32_e32 v110, v93, v110
	v_add_f32_e32 v110, v94, v110
	v_add_f32_e32 v110, v95, v110
	v_cvt_pk_bf16_f32 v114, v90, v91
	v_cvt_pk_bf16_f32 v115, v92, v93
	ds_read_b64_tr_b16 v[90:91], v203 offset:39936
	ds_read_b64_tr_b16 v[92:93], v203 offset:40448
	v_mfma_f32_32x32x16_bf16 v[50:65], v[154:157], v[118:121], v[50:65]
	v_add_f32_e32 v110, v96, v110
	v_add_f32_e32 v110, v97, v110
	v_cvt_pk_bf16_f32 v116, v94, v95
	v_cvt_pk_bf16_f32 v117, v96, v97
	s_add_i32 s98, s46, 0x4000
	s_mov_b32 s5, m0
	s_mov_b32 m0, s98
	s_nop 0
	global_load_lds_dwordx4 v189, s[100:101]
	s_mov_b32 m0, s5
	s_add_i32 s98, s47, 0x0
	s_mov_b32 s5, m0
	s_mov_b32 m0, s98
	s_nop 0
	global_load_lds_dwordx4 v187, s[100:101]
	s_mov_b32 m0, s5
	v_add_f32_e32 v205, v190, v110

.Lf3_1_485:
	s_waitcnt lgkmcnt(9)
	v_mfma_f32_32x32x16_bf16 v[98:113], v[174:177], v[142:145], v[34:49]
	ds_read_b64_tr_b16 v[178:179], v203 offset:40960
	ds_read_b64_tr_b16 v[180:181], v203 offset:41472
	v_add_f32_e32 v82, v66, v67
	v_add_f32_e32 v82, v68, v82
	v_add_f32_e32 v82, v69, v82
	v_add_f32_e32 v82, v70, v82
	v_add_f32_e32 v82, v71, v82
	v_cvt_pk_bf16_f32 v138, v66, v67
	v_cvt_pk_bf16_f32 v139, v68, v69
	ds_read_b64_tr_b16 v[174:175], v203 offset:45056
	ds_read_b64_tr_b16 v[176:177], v203 offset:45568
	v_add_f32_e32 v66, v72, v82
	s_waitcnt lgkmcnt(10)
	v_mfma_f32_32x32x16_bf16 v[82:97], v[170:173], v[142:145], v[34:49]
	v_add_f32_e32 v66, v73, v66
	v_add_f32_e32 v66, v74, v66
	v_add_f32_e32 v114, v75, v66
	v_cvt_pk_bf16_f32 v140, v70, v71
	v_cvt_pk_bf16_f32 v141, v72, v73
	ds_read_b64_tr_b16 v[66:67], v203 offset:41984
	ds_read_b64_tr_b16 v[68:69], v203 offset:42496
	s_waitcnt lgkmcnt(11)
	v_mfma_f32_32x32x16_bf16 v[98:113], v[166:169], v[134:137], v[98:113]
	v_add_f32_e32 v70, v76, v114
	v_add_f32_e32 v70, v77, v70
	v_add_f32_e32 v70, v78, v70
	v_add_f32_e32 v114, v79, v70
	v_cvt_pk_bf16_f32 v130, v74, v75
	v_cvt_pk_bf16_f32 v131, v76, v77
	ds_read_b64_tr_b16 v[70:71], v203 offset:46080
	ds_read_b64_tr_b16 v[72:73], v203 offset:46592
	s_waitcnt lgkmcnt(12)
	v_mfma_f32_32x32x16_bf16 v[82:97], v[162:165], v[134:137], v[82:97]
	v_add_f32_e32 v74, v80, v114
	v_add_f32_e32 v74, v81, v74
	v_add_f32_e32 v74, v50, v74
	v_add_f32_e32 v114, v51, v74
	v_cvt_pk_bf16_f32 v132, v78, v79
	v_cvt_pk_bf16_f32 v133, v80, v81
	ds_read_b64_tr_b16 v[74:75], v203 offset:43008
	ds_read_b64_tr_b16 v[76:77], v203 offset:43520
	s_waitcnt lgkmcnt(13)
	v_mfma_f32_32x32x16_bf16 v[98:113], v[158:161], v[126:129], v[98:113]
	v_add_f32_e32 v78, v52, v114
	v_add_f32_e32 v78, v53, v78
	v_add_f32_e32 v78, v54, v78
	v_add_f32_e32 v78, v55, v78
	v_cvt_pk_bf16_f32 v122, v50, v51
	v_cvt_pk_bf16_f32 v123, v52, v53
	ds_read_b64_tr_b16 v[50:51], v203 offset:47104
	ds_read_b64_tr_b16 v[52:53], v203 offset:47616
	s_waitcnt lgkmcnt(14)
	v_mfma_f32_32x32x16_bf16 v[82:97], v[154:157], v[126:129], v[82:97]
	v_add_f32_e32 v78, v56, v78
	v_add_f32_e32 v78, v57, v78
	v_add_f32_e32 v78, v58, v78
	v_add_f32_e32 v78, v59, v78
	v_cvt_pk_bf16_f32 v124, v54, v55
	v_cvt_pk_bf16_f32 v125, v56, v57
	ds_read_b64_tr_b16 v[54:55], v203 offset:44032
	ds_read_b64_tr_b16 v[56:57], v203 offset:44544
	s_waitcnt lgkmcnt(14)
	v_mfma_f32_32x32x16_bf16 v[98:113], v[150:153], v[118:121], v[98:113]
	v_add_f32_e32 v78, v60, v78
	v_add_f32_e32 v78, v61, v78
	v_add_f32_e32 v78, v62, v78
	v_add_f32_e32 v78, v63, v78
	v_cvt_pk_bf16_f32 v114, v58, v59
	v_cvt_pk_bf16_f32 v115, v60, v61
	ds_read_b64_tr_b16 v[58:59], v203 offset:48128
	ds_read_b64_tr_b16 v[60:61], v203 offset:48640
	v_mfma_f32_32x32x16_bf16 v[82:97], v[146:149], v[118:121], v[82:97]
	v_add_f32_e32 v78, v64, v78
	v_add_f32_e32 v78, v65, v78
	v_cvt_pk_bf16_f32 v116, v62, v63
	v_cvt_pk_bf16_f32 v117, v64, v65
	s_add_i32 s98, s46, 0x0
	s_mov_b32 s5, m0
	s_mov_b32 m0, s98
	s_nop 0
	global_load_lds_dwordx4 v188, s[100:101]
	s_mov_b32 m0, s5
	s_add_i32 s98, s47, 0x2000
	s_mov_b32 s5, m0
	s_mov_b32 m0, s98
	s_nop 0
	global_load_lds_dwordx4 v186, s[100:101]
	s_mov_b32 m0, s5
	v_add_f32_e32 v190, v205, v78

.Lf3_1_488:
	s_waitcnt lgkmcnt(9)
	v_mfma_f32_32x32x16_bf16 v[66:81], v[62:65], v[142:145], v[34:49]
	ds_read_b64_tr_b16 v[150:151], v203 offset:24576
	ds_read_b64_tr_b16 v[152:153], v203 offset:25088
	v_add_f32_e32 v50, v98, v99
	v_add_f32_e32 v50, v100, v50
	v_add_f32_e32 v50, v101, v50
	v_add_f32_e32 v50, v102, v50
	v_add_f32_e32 v50, v103, v50
	v_cvt_pk_bf16_f32 v138, v98, v99
	v_cvt_pk_bf16_f32 v139, v100, v101
	ds_read_b64_tr_b16 v[146:147], v203 offset:28672
	ds_read_b64_tr_b16 v[148:149], v203 offset:29184
	v_add_f32_e32 v50, v104, v50
	v_add_f32_e32 v50, v105, v50
	v_add_f32_e32 v50, v106, v50
	v_add_f32_e32 v114, v107, v50
	s_waitcnt lgkmcnt(10)
	v_mfma_f32_32x32x16_bf16 v[50:65], v[174:177], v[142:145], v[34:49]
	v_cvt_pk_bf16_f32 v140, v102, v103
	v_cvt_pk_bf16_f32 v141, v104, v105
	ds_read_b64_tr_b16 v[98:99], v203 offset:25600
	ds_read_b64_tr_b16 v[100:101], v203 offset:26112
	s_waitcnt lgkmcnt(11)
	v_mfma_f32_32x32x16_bf16 v[66:81], v[178:181], v[134:137], v[66:81]
	v_add_f32_e32 v102, v108, v114
	v_add_f32_e32 v102, v109, v102
	v_add_f32_e32 v102, v110, v102
	v_add_f32_e32 v114, v111, v102
	v_cvt_pk_bf16_f32 v130, v106, v107
	v_cvt_pk_bf16_f32 v131, v108, v109
	ds_read_b64_tr_b16 v[102:103], v203 offset:29696
	ds_read_b64_tr_b16 v[104:105], v203 offset:30208
	s_waitcnt lgkmcnt(12)
	v_mfma_f32_32x32x16_bf16 v[50:65], v[170:173], v[134:137], v[50:65]
	v_add_f32_e32 v106, v112, v114
	v_add_f32_e32 v106, v113, v106
	v_add_f32_e32 v106, v82, v106
	v_add_f32_e32 v114, v83, v106
	v_cvt_pk_bf16_f32 v132, v110, v111
	v_cvt_pk_bf16_f32 v133, v112, v113
	ds_read_b64_tr_b16 v[106:107], v203 offset:26624
	ds_read_b64_tr_b16 v[108:109], v203 offset:27136
	s_waitcnt lgkmcnt(13)
	v_mfma_f32_32x32x16_bf16 v[66:81], v[166:169], v[126:129], v[66:81]
	v_add_f32_e32 v110, v84, v114
	v_add_f32_e32 v110, v85, v110
	v_add_f32_e32 v110, v86, v110
	v_add_f32_e32 v110, v87, v110
	v_cvt_pk_bf16_f32 v122, v82, v83
	v_cvt_pk_bf16_f32 v123, v84, v85
	ds_read_b64_tr_b16 v[82:83], v203 offset:30720
	ds_read_b64_tr_b16 v[84:85], v203 offset:31232
	s_waitcnt lgkmcnt(14)
	v_mfma_f32_32x32x16_bf16 v[50:65], v[162:165], v[126:129], v[50:65]
	v_add_f32_e32 v110, v88, v110
	v_add_f32_e32 v110, v89, v110
	v_add_f32_e32 v110, v90, v110
	v_add_f32_e32 v110, v91, v110
	v_cvt_pk_bf16_f32 v124, v86, v87
	v_cvt_pk_bf16_f32 v125, v88, v89
	ds_read_b64_tr_b16 v[86:87], v203 offset:27648
	ds_read_b64_tr_b16 v[88:89], v203 offset:28160
	s_waitcnt lgkmcnt(14)
	v_mfma_f32_32x32x16_bf16 v[66:81], v[158:161], v[118:121], v[66:81]
	v_add_f32_e32 v110, v92, v110
	v_add_f32_e32 v110, v93, v110
	v_add_f32_e32 v110, v94, v110
	v_add_f32_e32 v110, v95, v110
	v_cvt_pk_bf16_f32 v114, v90, v91
	v_cvt_pk_bf16_f32 v115, v92, v93
	ds_read_b64_tr_b16 v[90:91], v203 offset:31744
	ds_read_b64_tr_b16 v[92:93], v203 offset:32256
	v_mfma_f32_32x32x16_bf16 v[50:65], v[154:157], v[118:121], v[50:65]
	v_add_f32_e32 v110, v96, v110
	v_add_f32_e32 v110, v97, v110
	v_cvt_pk_bf16_f32 v116, v94, v95
	v_cvt_pk_bf16_f32 v117, v96, v97
	s_add_i32 s98, s46, 0x2000
	s_mov_b32 s5, m0
	s_mov_b32 m0, s98
	s_nop 0
	global_load_lds_dwordx4 v189, s[100:101]
	s_mov_b32 m0, s5
	s_add_i32 s98, s47, 0x4000
	s_mov_b32 s5, m0
	s_mov_b32 m0, s98
	s_nop 0
	global_load_lds_dwordx4 v187, s[100:101]
	s_mov_b32 m0, s5
	v_add_f32_e32 v205, v190, v110

.Lf3_2_485:
	s_waitcnt lgkmcnt(9)
	v_mfma_f32_32x32x16_bf16 v[98:113], v[174:177], v[142:145], v[34:49]
	ds_read_b64_tr_b16 v[178:179], v203 offset:32768
	ds_read_b64_tr_b16 v[180:181], v203 offset:33280
	v_add_f32_e32 v82, v66, v67
	v_add_f32_e32 v82, v68, v82
	v_add_f32_e32 v82, v69, v82
	v_add_f32_e32 v82, v70, v82
	v_add_f32_e32 v82, v71, v82
	v_cvt_pk_bf16_f32 v138, v66, v67
	v_cvt_pk_bf16_f32 v139, v68, v69
	ds_read_b64_tr_b16 v[174:175], v203 offset:36864
	ds_read_b64_tr_b16 v[176:177], v203 offset:37376
	v_add_f32_e32 v66, v72, v82
	s_waitcnt lgkmcnt(10)
	v_mfma_f32_32x32x16_bf16 v[82:97], v[170:173], v[142:145], v[34:49]
	v_add_f32_e32 v66, v73, v66
	v_add_f32_e32 v66, v74, v66
	v_add_f32_e32 v114, v75, v66
	v_cvt_pk_bf16_f32 v140, v70, v71
	v_cvt_pk_bf16_f32 v141, v72, v73
	ds_read_b64_tr_b16 v[66:67], v203 offset:33792
	ds_read_b64_tr_b16 v[68:69], v203 offset:34304
	s_waitcnt lgkmcnt(11)
	v_mfma_f32_32x32x16_bf16 v[98:113], v[166:169], v[134:137], v[98:113]
	v_add_f32_e32 v70, v76, v114
	v_add_f32_e32 v70, v77, v70
	v_add_f32_e32 v70, v78, v70
	v_add_f32_e32 v114, v79, v70
	v_cvt_pk_bf16_f32 v130, v74, v75
	v_cvt_pk_bf16_f32 v131, v76, v77
	ds_read_b64_tr_b16 v[70:71], v203 offset:37888
	ds_read_b64_tr_b16 v[72:73], v203 offset:38400
	s_waitcnt lgkmcnt(12)
	v_mfma_f32_32x32x16_bf16 v[82:97], v[162:165], v[134:137], v[82:97]
	v_add_f32_e32 v74, v80, v114
	v_add_f32_e32 v74, v81, v74
	v_add_f32_e32 v74, v50, v74
	v_add_f32_e32 v114, v51, v74
	v_cvt_pk_bf16_f32 v132, v78, v79
	v_cvt_pk_bf16_f32 v133, v80, v81
	ds_read_b64_tr_b16 v[74:75], v203 offset:34816
	ds_read_b64_tr_b16 v[76:77], v203 offset:35328
	s_waitcnt lgkmcnt(13)
	v_mfma_f32_32x32x16_bf16 v[98:113], v[158:161], v[126:129], v[98:113]
	v_add_f32_e32 v78, v52, v114
	v_add_f32_e32 v78, v53, v78
	v_add_f32_e32 v78, v54, v78
	v_add_f32_e32 v78, v55, v78
	v_cvt_pk_bf16_f32 v122, v50, v51
	v_cvt_pk_bf16_f32 v123, v52, v53
	ds_read_b64_tr_b16 v[50:51], v203 offset:38912
	ds_read_b64_tr_b16 v[52:53], v203 offset:39424
	s_waitcnt lgkmcnt(14)
	v_mfma_f32_32x32x16_bf16 v[82:97], v[154:157], v[126:129], v[82:97]
	v_add_f32_e32 v78, v56, v78
	v_add_f32_e32 v78, v57, v78
	v_add_f32_e32 v78, v58, v78
	v_add_f32_e32 v78, v59, v78
	v_cvt_pk_bf16_f32 v124, v54, v55
	v_cvt_pk_bf16_f32 v125, v56, v57
	ds_read_b64_tr_b16 v[54:55], v203 offset:35840
	ds_read_b64_tr_b16 v[56:57], v203 offset:36352
	s_waitcnt lgkmcnt(14)
	v_mfma_f32_32x32x16_bf16 v[98:113], v[150:153], v[118:121], v[98:113]
	v_add_f32_e32 v78, v60, v78
	v_add_f32_e32 v78, v61, v78
	v_add_f32_e32 v78, v62, v78
	v_add_f32_e32 v78, v63, v78
	v_cvt_pk_bf16_f32 v114, v58, v59
	v_cvt_pk_bf16_f32 v115, v60, v61
	ds_read_b64_tr_b16 v[58:59], v203 offset:39936
	ds_read_b64_tr_b16 v[60:61], v203 offset:40448
	v_mfma_f32_32x32x16_bf16 v[82:97], v[146:149], v[118:121], v[82:97]
	v_add_f32_e32 v78, v64, v78
	v_add_f32_e32 v78, v65, v78
	v_cvt_pk_bf16_f32 v116, v62, v63
	v_cvt_pk_bf16_f32 v117, v64, v65
	s_add_i32 s98, s46, 0x4000
	s_mov_b32 s5, m0
	s_mov_b32 m0, s98
	s_nop 0
	global_load_lds_dwordx4 v188, s[100:101]
	s_mov_b32 m0, s5
	s_add_i32 s98, s47, 0x0
	s_mov_b32 s5, m0
	s_mov_b32 m0, s98
	s_nop 0
	global_load_lds_dwordx4 v186, s[100:101]
	s_mov_b32 m0, s5
	v_add_f32_e32 v190, v205, v78

.Lf3_2_488:
	s_waitcnt lgkmcnt(9)
	v_mfma_f32_32x32x16_bf16 v[66:81], v[62:65], v[142:145], v[34:49]
	ds_read_b64_tr_b16 v[150:151], v203 offset:40960
	ds_read_b64_tr_b16 v[152:153], v203 offset:41472
	v_add_f32_e32 v50, v98, v99
	v_add_f32_e32 v50, v100, v50
	v_add_f32_e32 v50, v101, v50
	v_add_f32_e32 v50, v102, v50
	v_add_f32_e32 v50, v103, v50
	v_cvt_pk_bf16_f32 v138, v98, v99
	v_cvt_pk_bf16_f32 v139, v100, v101
	ds_read_b64_tr_b16 v[146:147], v203 offset:45056
	ds_read_b64_tr_b16 v[148:149], v203 offset:45568
	v_add_f32_e32 v50, v104, v50
	v_add_f32_e32 v50, v105, v50
	v_add_f32_e32 v50, v106, v50
	v_add_f32_e32 v114, v107, v50
	s_waitcnt lgkmcnt(10)
	v_mfma_f32_32x32x16_bf16 v[50:65], v[174:177], v[142:145], v[34:49]
	v_cvt_pk_bf16_f32 v140, v102, v103
	v_cvt_pk_bf16_f32 v141, v104, v105
	ds_read_b64_tr_b16 v[98:99], v203 offset:41984
	ds_read_b64_tr_b16 v[100:101], v203 offset:42496
	s_waitcnt lgkmcnt(11)
	v_mfma_f32_32x32x16_bf16 v[66:81], v[178:181], v[134:137], v[66:81]
	v_add_f32_e32 v102, v108, v114
	v_add_f32_e32 v102, v109, v102
	v_add_f32_e32 v102, v110, v102
	v_add_f32_e32 v114, v111, v102
	v_cvt_pk_bf16_f32 v130, v106, v107
	v_cvt_pk_bf16_f32 v131, v108, v109
	ds_read_b64_tr_b16 v[102:103], v203 offset:46080
	ds_read_b64_tr_b16 v[104:105], v203 offset:46592
	s_waitcnt lgkmcnt(12)
	v_mfma_f32_32x32x16_bf16 v[50:65], v[170:173], v[134:137], v[50:65]
	v_add_f32_e32 v106, v112, v114
	v_add_f32_e32 v106, v113, v106
	v_add_f32_e32 v106, v82, v106
	v_add_f32_e32 v114, v83, v106
	v_cvt_pk_bf16_f32 v132, v110, v111
	v_cvt_pk_bf16_f32 v133, v112, v113
	ds_read_b64_tr_b16 v[106:107], v203 offset:43008
	ds_read_b64_tr_b16 v[108:109], v203 offset:43520
	s_waitcnt lgkmcnt(13)
	v_mfma_f32_32x32x16_bf16 v[66:81], v[166:169], v[126:129], v[66:81]
	v_add_f32_e32 v110, v84, v114
	v_add_f32_e32 v110, v85, v110
	v_add_f32_e32 v110, v86, v110
	v_add_f32_e32 v110, v87, v110
	v_cvt_pk_bf16_f32 v122, v82, v83
	v_cvt_pk_bf16_f32 v123, v84, v85
	ds_read_b64_tr_b16 v[82:83], v203 offset:47104
	ds_read_b64_tr_b16 v[84:85], v203 offset:47616
	s_waitcnt lgkmcnt(14)
	v_mfma_f32_32x32x16_bf16 v[50:65], v[162:165], v[126:129], v[50:65]
	v_add_f32_e32 v110, v88, v110
	v_add_f32_e32 v110, v89, v110
	v_add_f32_e32 v110, v90, v110
	v_add_f32_e32 v110, v91, v110
	v_cvt_pk_bf16_f32 v124, v86, v87
	v_cvt_pk_bf16_f32 v125, v88, v89
	ds_read_b64_tr_b16 v[86:87], v203 offset:44032
	ds_read_b64_tr_b16 v[88:89], v203 offset:44544
	s_waitcnt lgkmcnt(14)
	v_mfma_f32_32x32x16_bf16 v[66:81], v[158:161], v[118:121], v[66:81]
	v_add_f32_e32 v110, v92, v110
	v_add_f32_e32 v110, v93, v110
	v_add_f32_e32 v110, v94, v110
	v_add_f32_e32 v110, v95, v110
	v_cvt_pk_bf16_f32 v114, v90, v91
	v_cvt_pk_bf16_f32 v115, v92, v93
	ds_read_b64_tr_b16 v[90:91], v203 offset:48128
	ds_read_b64_tr_b16 v[92:93], v203 offset:48640
	v_mfma_f32_32x32x16_bf16 v[50:65], v[154:157], v[118:121], v[50:65]
	v_add_f32_e32 v110, v96, v110
	v_add_f32_e32 v110, v97, v110
	v_cvt_pk_bf16_f32 v116, v94, v95
	v_cvt_pk_bf16_f32 v117, v96, v97
	s_add_i32 s98, s46, 0x0
	s_mov_b32 s5, m0
	s_mov_b32 m0, s98
	s_nop 0
	global_load_lds_dwordx4 v189, s[100:101]
	s_mov_b32 m0, s5
	s_add_i32 s98, s47, 0x2000
	s_mov_b32 s5, m0
	s_mov_b32 m0, s98
	s_nop 0
	global_load_lds_dwordx4 v187, s[100:101]
	s_mov_b32 m0, s5
	v_add_f32_e32 v205, v190, v110
